# P6 fused epilogue pass 1 (X1B stores) also through cross-wave LDS exchange (padded 528B rows at LDS 0x21000), on top of pass-2 and P8 row-stores
# baseline (speedup 1.0000x reference)
.LBB0_1482:
	s_lshr_b32 s17, s46, 4
	s_mul_i32 s48, s17, 0xc00
	s_ashr_i32 s49, s48, 31
	v_lshl_or_b32 v208, s44, 8, v230
	s_lshl_b64 s[48:49], s[48:49], 2
	s_add_u32 s50, s78, s48
	v_ashrrev_i32_e32 v209, 31, v208
	s_addc_u32 s51, s79, s49
	v_lshlrev_b64 v[216:217], 2, v[208:209]
	v_lshl_add_u32 v218, s46, 8, v228
	v_lshl_add_u64 v[112:113], s[50:51], 0, v[216:217]
	s_mov_b64 s[50:51], 0x1502000
	s_mov_b32 s17, 0x1502000
	v_ashrrev_i32_e32 v219, 31, v218
	v_lshl_add_u64 v[114:115], v[112:113], 0, s[50:51]
	v_add_co_u32_e32 v112, vcc, s17, v112
	v_lshl_add_u64 v[220:221], s[52:53], 0, v[216:217]
	v_lshlrev_b64 v[116:117], 12, v[218:219]
	v_addc_co_u32_e32 v113, vcc, 0, v113, vcc
	v_lshl_add_u64 v[144:145], v[220:221], 0, v[116:117]
	global_load_dwordx4 v[224:227], v[144:145], off offset:16
	global_load_dwordx4 v[124:127], v[114:115], off offset:16
	global_load_dwordx4 v[116:119], v[114:115], off offset:512
	global_load_dwordx4 v[240:243], v[144:145], off offset:512
	global_load_dwordx4 v[128:131], v[112:113], off
	global_load_dwordx4 v[244:247], v[144:145], off
	global_load_dwordx4 v[248:251], v[144:145], off offset:528
	s_nop 0
	global_load_dwordx4 v[112:115], v[114:115], off offset:528
	v_or_b32_e32 v210, 16, v218
	v_ashrrev_i32_e32 v211, 31, v210
	v_lshlrev_b64 v[144:145], 12, v[210:211]
	v_or_b32_e32 v214, 32, v218
	v_lshl_add_u64 v[144:145], v[220:221], 0, v[144:145]
	v_ashrrev_i32_e32 v215, 31, v214
	global_load_dwordx4 v[184:187], v[144:145], off offset:16
	global_load_dwordx4 v[188:191], v[144:145], off
	global_load_dwordx4 v[172:175], v[144:145], off offset:528
	global_load_dwordx4 v[176:179], v[144:145], off offset:512
	v_lshlrev_b64 v[144:145], 12, v[214:215]
	v_or_b32_e32 v222, 48, v218
	v_lshl_add_u64 v[144:145], v[220:221], 0, v[144:145]
	v_ashrrev_i32_e32 v223, 31, v222
	global_load_dwordx4 v[168:171], v[144:145], off offset:16
	global_load_dwordx4 v[180:183], v[144:145], off
	global_load_dwordx4 v[160:163], v[144:145], off offset:528
	global_load_dwordx4 v[164:167], v[144:145], off offset:512
	v_lshlrev_b64 v[144:145], 12, v[222:223]
	v_lshl_add_u64 v[148:149], v[220:221], 0, v[144:145]
	global_load_dwordx4 v[152:155], v[148:149], off offset:16
	global_load_dwordx4 v[156:159], v[148:149], off
	global_load_dwordx4 v[144:147], v[148:149], off offset:528
	s_nop 0
	global_load_dwordx4 v[148:151], v[148:149], off offset:512
	v_and_b32_e32 v212, 64, v236
	v_xor_b32_e32 v238, 16, v236
	v_add_u32_e32 v252, 64, v212
	v_cmp_lt_i32_e32 vcc, v238, v252
	v_xor_b32_e32 v239, 32, v236
	v_lshlrev_b64 v[212:213], 11, v[218:219]
	v_cndmask_b32_e32 v238, v236, v238, vcc
	v_lshlrev_b32_e32 v238, 2, v238
	v_cmp_lt_i32_e32 vcc, v239, v252
	v_lshl_add_u64 v[252:253], s[6:7], 0, v[212:213]
	v_lshl_add_u64 v[252:253], v[208:209], 1, v[252:253]
	v_cndmask_b32_e32 v239, v236, v239, vcc
	v_lshlrev_b32_e32 v239, 2, v239
	s_waitcnt vmcnt(0)
	v_pk_fma_f32 v[138:139], v[138:139], v[126:127], v[226:227]
	v_pk_fma_f32 v[136:137], v[136:137], v[124:125], v[224:225]
	v_pk_fma_f32 v[226:227], v[8:9], v[116:117], v[240:241]
	v_pk_fma_f32 v[224:225], v[10:11], v[118:119], v[242:243]
	v_pk_fma_f32 v[140:141], v[140:141], v[128:129], v[244:245]
	v_pk_fma_f32 v[10:11], v[142:143], v[130:131], v[246:247]
	v_pk_fma_f32 v[142:143], v[6:7], v[114:115], v[250:251]
	v_pk_fma_f32 v[6:7], v[4:5], v[112:113], v[248:249]
	v_and_b32_e32 v244, 15, v228
	v_lshrrev_b32_e32 v245, 6, v228
	v_lshl_add_u32 v246, v245, 4, v244
	v_mul_u32_u24_e32 v246, 0x210, v246
	v_lshrrev_b32_e32 v247, 3, v230
	v_lshl_add_u32 v246, v247, 4, v246
	v_add_u32_e32 v240, 0x21000, v246
	v_lshrrev_b32_e32 v247, 5, v230
	v_lshrrev_b32_e32 v248, 5, v236
	v_lshl_add_u32 v247, v247, 2, v248
	v_lshl_add_u32 v248, v245, 4, v247
	v_mul_u32_u24_e32 v248, 0x210, v248
	v_and_b32_e32 v249, 31, v236
	v_lshl_add_u32 v248, v249, 4, v248
	v_add_u32_e32 v241, 0x21000, v248
	v_sub_u32_e32 v250, v247, v244
	v_lshlrev_b32_e32 v250, 11, v250
	v_lshlrev_b32_e32 v249, 3, v249
	v_sub_u32_e32 v249, v249, v230
	v_lshl_add_u32 v242, v249, 1, v250
	v_add_u32_e32 v242, 0x800, v242
	v_ashrrev_i32_e32 v243, 31, v242
	v_mul_f32_e32 v4, v227, v227
	v_mul_f32_e32 v5, v141, v141
	v_fmac_f32_e32 v4, v226, v226
	v_fmac_f32_e32 v5, v140, v140
	v_fmac_f32_e32 v4, v224, v224
	v_fmac_f32_e32 v5, v10, v10
	v_fmac_f32_e32 v4, v225, v225
	v_fmac_f32_e32 v5, v11, v11
	v_fmac_f32_e32 v4, v6, v6
	v_fmac_f32_e32 v5, v136, v136
	v_fmac_f32_e32 v4, v7, v7
	v_fmac_f32_e32 v5, v137, v137
	v_fmac_f32_e32 v4, v142, v142
	v_fmac_f32_e32 v5, v138, v138
	v_fmac_f32_e32 v4, v143, v143
	v_fmac_f32_e32 v5, v139, v139
	v_add_f32_e32 v5, v5, v4
	v_cvt_pk_bf16_f32 v8, v140, v141
	ds_bpermute_b32 v140, v238, v5
	v_cvt_pk_bf16_f32 v9, v10, v11
	v_cvt_pk_bf16_f32 v10, v136, v137
	v_cvt_pk_bf16_f32 v11, v138, v139
	ds_write_b128 v240, v[8:11]
	s_waitcnt lgkmcnt(0)
	v_add_f32_e32 v136, v5, v140
	ds_bpermute_b32 v137, v239, v136
	v_cvt_pk_bf16_f32 v4, v226, v227
	v_cvt_pk_bf16_f32 v5, v224, v225
	v_cvt_pk_bf16_f32 v6, v6, v7
	v_cvt_pk_bf16_f32 v7, v142, v143
	ds_write_b128 v240, v[4:7] offset:256
	v_lshl_add_u64 v[252:253], v[252:253], 0, v[242:243]
	s_waitcnt lgkmcnt(0)
	s_barrier
	ds_read_b128 v[244:247], v241
	ds_read_b128 v[248:251], v241 offset:1056
	s_waitcnt lgkmcnt(0)
	s_barrier
	global_store_dwordx4 v[252:253], v[244:247], off offset:-2048
	global_store_dwordx4 v[252:253], v[248:251], off offset:2048
	s_and_saveexec_b64 s[50:51], s[0:1]
	s_cbranch_execz .LBB0_1484
	s_waitcnt lgkmcnt(0)
	v_add_f32_e32 v136, v136, v137
	ds_write_b32 v231, v136
.LBB0_1484:
	s_or_b64 exec, exec, s[50:51]
	v_pk_fma_f32 v[132:133], v[132:133], v[128:129], v[188:189]
	v_pk_fma_f32 v[120:121], v[120:121], v[116:117], v[176:177]
	v_mul_f32_e32 v140, v133, v133
	v_pk_fma_f32 v[138:139], v[0:1], v[124:125], v[184:185]
	v_cvt_pk_bf16_f32 v0, v132, v133
	v_fmac_f32_e32 v140, v132, v132
	v_pk_fma_f32 v[132:133], v[14:15], v[114:115], v[174:175]
	v_pk_fma_f32 v[14:15], v[12:13], v[112:113], v[172:173]
	v_mul_f32_e32 v12, v121, v121
	v_pk_fma_f32 v[134:135], v[134:135], v[130:131], v[190:191]
	v_pk_fma_f32 v[122:123], v[122:123], v[118:119], v[178:179]
	v_fmac_f32_e32 v12, v120, v120
	v_fmac_f32_e32 v140, v134, v134
	v_fmac_f32_e32 v12, v122, v122
	v_fmac_f32_e32 v140, v135, v135
	v_fmac_f32_e32 v12, v123, v123
	v_fmac_f32_e32 v140, v138, v138
	v_fmac_f32_e32 v12, v14, v14
	s_waitcnt lgkmcnt(0)
	v_pk_fma_f32 v[136:137], v[2:3], v[126:127], v[186:187]
	v_fmac_f32_e32 v140, v139, v139
	v_fmac_f32_e32 v12, v15, v15
	v_fmac_f32_e32 v140, v136, v136
	v_fmac_f32_e32 v12, v132, v132
	v_fmac_f32_e32 v140, v137, v137
	v_fmac_f32_e32 v12, v133, v133
	v_cvt_pk_bf16_f32 v1, v134, v135
	v_cvt_pk_bf16_f32 v2, v138, v139
	v_cvt_pk_bf16_f32 v3, v136, v137
	v_add_f32_e32 v136, v140, v12
	ds_bpermute_b32 v137, v238, v136
	v_lshlrev_b64 v[210:211], 11, v[210:211]
	v_lshl_add_u64 v[12:13], s[6:7], 0, v[210:211]
	v_lshl_add_u64 v[134:135], v[208:209], 1, v[12:13]
	ds_write_b128 v240, v[0:3]
	v_cvt_pk_bf16_f32 v12, v120, v121
	s_waitcnt lgkmcnt(0)
	v_add_f32_e32 v120, v136, v137
	ds_bpermute_b32 v121, v239, v120
	v_cvt_pk_bf16_f32 v13, v122, v123
	v_cvt_pk_bf16_f32 v14, v14, v15
	v_cvt_pk_bf16_f32 v15, v132, v133
	ds_write_b128 v240, v[12:15] offset:256
	v_lshl_add_u64 v[252:253], v[134:135], 0, v[242:243]
	s_waitcnt lgkmcnt(0)
	s_barrier
	ds_read_b128 v[244:247], v241
	ds_read_b128 v[248:251], v241 offset:1056
	s_waitcnt lgkmcnt(0)
	s_barrier
	global_store_dwordx4 v[252:253], v[244:247], off offset:-2048
	global_store_dwordx4 v[252:253], v[248:251], off offset:2048
	s_and_saveexec_b64 s[50:51], s[0:1]
	s_cbranch_execz .LBB0_1486
	s_waitcnt lgkmcnt(0)
	v_add_f32_e32 v120, v120, v121
	ds_write_b32 v231, v120 offset:64
.LBB0_1486:
	s_or_b64 exec, exec, s[50:51]
	v_add_u32_e32 v226, 0x80, v218
	v_ashrrev_i32_e32 v227, 31, v226
	s_waitcnt lgkmcnt(0)
	v_lshlrev_b64 v[120:121], 12, v[226:227]
	v_add_u32_e32 v224, 0x90, v218
	v_lshl_add_u64 v[120:121], v[220:221], 0, v[120:121]
	v_ashrrev_i32_e32 v225, 31, v224
	global_load_dwordx4 v[184:187], v[120:121], off offset:16
	global_load_dwordx4 v[188:191], v[120:121], off
	global_load_dwordx4 v[172:175], v[120:121], off offset:528
	global_load_dwordx4 v[176:179], v[120:121], off offset:512
	v_lshlrev_b64 v[120:121], 12, v[224:225]
	v_lshl_add_u64 v[132:133], v[220:221], 0, v[120:121]
	global_load_dwordx4 v[136:139], v[132:133], off offset:16
	global_load_dwordx4 v[140:143], v[132:133], off
	global_load_dwordx4 v[120:123], v[132:133], off offset:528
	s_nop 0
	global_load_dwordx4 v[132:135], v[132:133], off offset:512
	v_pk_fma_f32 v[108:109], v[108:109], v[128:129], v[180:181]
	v_pk_fma_f32 v[104:105], v[104:105], v[116:117], v[164:165]
	v_mul_f32_e32 v180, v109, v109
	v_pk_fma_f32 v[168:169], v[16:17], v[124:125], v[168:169]
	v_cvt_pk_bf16_f32 v16, v108, v109
	v_fmac_f32_e32 v180, v108, v108
	v_pk_fma_f32 v[108:109], v[26:27], v[114:115], v[162:163]
	v_pk_fma_f32 v[26:27], v[24:25], v[112:113], v[160:161]
	v_mul_f32_e32 v24, v105, v105
	v_pk_fma_f32 v[110:111], v[110:111], v[130:131], v[182:183]
	v_pk_fma_f32 v[106:107], v[106:107], v[118:119], v[166:167]
	v_fmac_f32_e32 v24, v104, v104
	v_fmac_f32_e32 v180, v110, v110
	v_fmac_f32_e32 v24, v106, v106
	v_fmac_f32_e32 v180, v111, v111
	v_fmac_f32_e32 v24, v107, v107
	v_fmac_f32_e32 v180, v168, v168
	v_fmac_f32_e32 v24, v26, v26
	v_pk_fma_f32 v[170:171], v[18:19], v[126:127], v[170:171]
	v_fmac_f32_e32 v180, v169, v169
	v_fmac_f32_e32 v24, v27, v27
	v_fmac_f32_e32 v180, v170, v170
	v_fmac_f32_e32 v24, v108, v108
	v_fmac_f32_e32 v180, v171, v171
	v_fmac_f32_e32 v24, v109, v109
	v_add_f32_e32 v160, v180, v24
	ds_bpermute_b32 v161, v238, v160
	v_lshlrev_b64 v[214:215], 11, v[214:215]
	v_lshl_add_u64 v[24:25], s[6:7], 0, v[214:215]
	v_cvt_pk_bf16_f32 v17, v110, v111
	v_lshl_add_u64 v[110:111], v[208:209], 1, v[24:25]
	v_cvt_pk_bf16_f32 v18, v168, v169
	v_cvt_pk_bf16_f32 v19, v170, v171
	ds_write_b128 v240, v[16:19]
	v_cvt_pk_bf16_f32 v24, v104, v105
	s_waitcnt lgkmcnt(0)
	v_add_f32_e32 v104, v160, v161
	ds_bpermute_b32 v105, v239, v104
	v_cvt_pk_bf16_f32 v25, v106, v107
	v_cvt_pk_bf16_f32 v26, v26, v27
	v_cvt_pk_bf16_f32 v27, v108, v109
	ds_write_b128 v240, v[24:27] offset:256
	v_lshl_add_u64 v[252:253], v[110:111], 0, v[242:243]
	s_waitcnt lgkmcnt(0)
	s_barrier
	ds_read_b128 v[244:247], v241
	ds_read_b128 v[248:251], v241 offset:1056
	s_waitcnt lgkmcnt(0)
	s_barrier
	global_store_dwordx4 v[252:253], v[244:247], off offset:-2048
	global_store_dwordx4 v[252:253], v[248:251], off offset:2048
	s_and_saveexec_b64 s[50:51], s[0:1]
	s_cbranch_execz .LBB0_1488
	s_waitcnt lgkmcnt(0)
	v_add_f32_e32 v104, v104, v105
	ds_write_b32 v231, v104 offset:128
.LBB0_1488:
	s_or_b64 exec, exec, s[50:51]
	v_pk_fma_f32 v[100:101], v[100:101], v[128:129], v[156:157]
	v_pk_fma_f32 v[96:97], v[96:97], v[116:117], v[148:149]
	v_mul_f32_e32 v108, v101, v101
	v_pk_fma_f32 v[106:107], v[20:21], v[124:125], v[152:153]
	v_cvt_pk_bf16_f32 v20, v100, v101
	v_fmac_f32_e32 v108, v100, v100
	v_pk_fma_f32 v[100:101], v[30:31], v[114:115], v[146:147]
	v_pk_fma_f32 v[30:31], v[28:29], v[112:113], v[144:145]
	v_mul_f32_e32 v28, v97, v97
	v_pk_fma_f32 v[102:103], v[102:103], v[130:131], v[158:159]
	v_pk_fma_f32 v[98:99], v[98:99], v[118:119], v[150:151]
	v_fmac_f32_e32 v28, v96, v96
	v_fmac_f32_e32 v108, v102, v102
	v_fmac_f32_e32 v28, v98, v98
	v_fmac_f32_e32 v108, v103, v103
	v_fmac_f32_e32 v28, v99, v99
	v_fmac_f32_e32 v108, v106, v106
	v_fmac_f32_e32 v28, v30, v30
	s_waitcnt lgkmcnt(0)
	v_pk_fma_f32 v[104:105], v[22:23], v[126:127], v[154:155]
	v_fmac_f32_e32 v108, v107, v107
	v_fmac_f32_e32 v28, v31, v31
	v_fmac_f32_e32 v108, v104, v104
	v_fmac_f32_e32 v28, v100, v100
	v_fmac_f32_e32 v108, v105, v105
	v_fmac_f32_e32 v28, v101, v101
	v_cvt_pk_bf16_f32 v21, v102, v103
	v_cvt_pk_bf16_f32 v22, v106, v107
	v_cvt_pk_bf16_f32 v23, v104, v105
	v_add_f32_e32 v104, v108, v28
	ds_bpermute_b32 v105, v238, v104
	v_lshlrev_b64 v[160:161], 11, v[222:223]
	v_lshl_add_u64 v[28:29], s[6:7], 0, v[160:161]
	v_lshl_add_u64 v[102:103], v[208:209], 1, v[28:29]
	ds_write_b128 v240, v[20:23]
	v_cvt_pk_bf16_f32 v28, v96, v97
	s_waitcnt lgkmcnt(0)
	v_add_f32_e32 v96, v104, v105
	ds_bpermute_b32 v97, v239, v96
	v_cvt_pk_bf16_f32 v29, v98, v99
	v_cvt_pk_bf16_f32 v30, v30, v31
	v_cvt_pk_bf16_f32 v31, v100, v101
	ds_write_b128 v240, v[28:31] offset:256
	v_lshl_add_u64 v[252:253], v[102:103], 0, v[242:243]
	s_waitcnt lgkmcnt(0)
	s_barrier
	ds_read_b128 v[244:247], v241
	ds_read_b128 v[248:251], v241 offset:1056
	s_waitcnt lgkmcnt(0)
	s_barrier
	global_store_dwordx4 v[252:253], v[244:247], off offset:-2048
	global_store_dwordx4 v[252:253], v[248:251], off offset:2048
	s_and_saveexec_b64 s[50:51], s[0:1]
	s_cbranch_execz .LBB0_1490
	s_waitcnt lgkmcnt(0)
	v_add_f32_e32 v96, v96, v97
	ds_write_b32 v231, v96 offset:192
.LBB0_1490:
	s_or_b64 exec, exec, s[50:51]
	v_or_b32_e32 v96, 32, v226
	s_waitcnt lgkmcnt(0)
	v_ashrrev_i32_e32 v97, 31, v96
	v_lshlrev_b64 v[96:97], 12, v[96:97]
	v_add_u32_e32 v166, 0xb0, v218
	v_lshl_add_u64 v[96:97], v[220:221], 0, v[96:97]
	v_ashrrev_i32_e32 v167, 31, v166
	global_load_dwordx4 v[152:155], v[96:97], off offset:16
	global_load_dwordx4 v[156:159], v[96:97], off
	global_load_dwordx4 v[144:147], v[96:97], off offset:528
	global_load_dwordx4 v[148:151], v[96:97], off offset:512
	v_lshlrev_b64 v[96:97], 12, v[166:167]
	v_lshl_add_u64 v[100:101], v[220:221], 0, v[96:97]
	global_load_dwordx4 v[104:107], v[100:101], off offset:16
	global_load_dwordx4 v[108:111], v[100:101], off
	global_load_dwordx4 v[96:99], v[100:101], off offset:528
	s_nop 0
	global_load_dwordx4 v[100:103], v[100:101], off offset:512
	s_waitcnt vmcnt(18)
	v_pk_fma_f32 v[92:93], v[92:93], v[128:129], v[188:189]
	s_waitcnt vmcnt(16)
	v_pk_fma_f32 v[88:89], v[88:89], v[116:117], v[176:177]
	v_mul_f32_e32 v170, v93, v93
	v_pk_fma_f32 v[168:169], v[32:33], v[124:125], v[184:185]
	v_cvt_pk_bf16_f32 v32, v92, v93
	v_fmac_f32_e32 v170, v92, v92
	v_pk_fma_f32 v[92:93], v[50:51], v[114:115], v[174:175]
	v_pk_fma_f32 v[50:51], v[48:49], v[112:113], v[172:173]
	v_mul_f32_e32 v48, v89, v89
	v_pk_fma_f32 v[94:95], v[94:95], v[130:131], v[190:191]
	v_pk_fma_f32 v[90:91], v[90:91], v[118:119], v[178:179]
	v_fmac_f32_e32 v48, v88, v88
	v_fmac_f32_e32 v170, v94, v94
	v_fmac_f32_e32 v48, v90, v90
	v_fmac_f32_e32 v170, v95, v95
	v_fmac_f32_e32 v48, v91, v91
	v_fmac_f32_e32 v170, v168, v168
	v_fmac_f32_e32 v48, v50, v50
	v_pk_fma_f32 v[164:165], v[34:35], v[126:127], v[186:187]
	v_fmac_f32_e32 v170, v169, v169
	v_fmac_f32_e32 v48, v51, v51
	v_fmac_f32_e32 v170, v164, v164
	v_fmac_f32_e32 v48, v92, v92
	v_fmac_f32_e32 v170, v165, v165
	v_fmac_f32_e32 v48, v93, v93
	v_cvt_pk_bf16_f32 v33, v94, v95
	v_cvt_pk_bf16_f32 v34, v168, v169
	v_cvt_pk_bf16_f32 v35, v164, v165
	v_add_f32_e32 v164, v170, v48
	ds_bpermute_b32 v165, v238, v164
	v_lshlrev_b64 v[162:163], 11, v[226:227]
	v_lshl_add_u64 v[48:49], s[6:7], 0, v[162:163]
	v_lshl_add_u64 v[94:95], v[208:209], 1, v[48:49]
	ds_write_b128 v240, v[32:35]
	v_cvt_pk_bf16_f32 v48, v88, v89
	s_waitcnt lgkmcnt(0)
	v_add_f32_e32 v88, v164, v165
	ds_bpermute_b32 v89, v239, v88
	v_cvt_pk_bf16_f32 v49, v90, v91
	v_cvt_pk_bf16_f32 v50, v50, v51
	v_cvt_pk_bf16_f32 v51, v92, v93
	ds_write_b128 v240, v[48:51] offset:256
	v_lshl_add_u64 v[252:253], v[94:95], 0, v[242:243]
	s_waitcnt lgkmcnt(0)
	s_barrier
	ds_read_b128 v[244:247], v241
	ds_read_b128 v[248:251], v241 offset:1056
	s_waitcnt lgkmcnt(0)
	s_barrier
	global_store_dwordx4 v[252:253], v[244:247], off offset:-2048
	global_store_dwordx4 v[252:253], v[248:251], off offset:2048
	s_and_saveexec_b64 s[50:51], s[0:1]
	s_cbranch_execz .LBB0_1492
	s_waitcnt lgkmcnt(0)
	v_add_f32_e32 v88, v88, v89
	ds_write_b32 v231, v88 offset:256
.LBB0_1492:
	s_or_b64 exec, exec, s[50:51]
	s_waitcnt vmcnt(16)
	v_pk_fma_f32 v[84:85], v[84:85], v[128:129], v[140:141]
	s_waitcnt vmcnt(14)
	v_pk_fma_f32 v[80:81], v[80:81], v[116:117], v[132:133]
	v_mul_f32_e32 v92, v85, v85
	v_pk_fma_f32 v[90:91], v[44:45], v[124:125], v[136:137]
	v_cvt_pk_bf16_f32 v44, v84, v85
	v_fmac_f32_e32 v92, v84, v84
	v_pk_fma_f32 v[84:85], v[54:55], v[114:115], v[122:123]
	v_pk_fma_f32 v[54:55], v[52:53], v[112:113], v[120:121]
	v_mul_f32_e32 v52, v81, v81
	v_pk_fma_f32 v[86:87], v[86:87], v[130:131], v[142:143]
	v_pk_fma_f32 v[82:83], v[82:83], v[118:119], v[134:135]
	v_fmac_f32_e32 v52, v80, v80
	v_fmac_f32_e32 v92, v86, v86
	v_fmac_f32_e32 v52, v82, v82
	v_fmac_f32_e32 v92, v87, v87
	v_fmac_f32_e32 v52, v83, v83
	v_fmac_f32_e32 v92, v90, v90
	v_fmac_f32_e32 v52, v54, v54
	s_waitcnt lgkmcnt(0)
	v_pk_fma_f32 v[88:89], v[46:47], v[126:127], v[138:139]
	v_fmac_f32_e32 v92, v91, v91
	v_fmac_f32_e32 v52, v55, v55
	v_fmac_f32_e32 v92, v88, v88
	v_fmac_f32_e32 v52, v84, v84
	v_fmac_f32_e32 v92, v89, v89
	v_fmac_f32_e32 v52, v85, v85
	v_cvt_pk_bf16_f32 v45, v86, v87
	v_cvt_pk_bf16_f32 v46, v90, v91
	v_cvt_pk_bf16_f32 v47, v88, v89
	v_add_f32_e32 v88, v92, v52
	ds_bpermute_b32 v89, v238, v88
	v_lshlrev_b64 v[164:165], 11, v[224:225]
	v_lshl_add_u64 v[52:53], s[6:7], 0, v[164:165]
	v_lshl_add_u64 v[86:87], v[208:209], 1, v[52:53]
	ds_write_b128 v240, v[44:47]
	v_cvt_pk_bf16_f32 v52, v80, v81
	s_waitcnt lgkmcnt(0)
	v_add_f32_e32 v80, v88, v89
	ds_bpermute_b32 v81, v239, v80
	v_cvt_pk_bf16_f32 v53, v82, v83
	v_cvt_pk_bf16_f32 v54, v54, v55
	v_cvt_pk_bf16_f32 v55, v84, v85
	ds_write_b128 v240, v[52:55] offset:256
	v_lshl_add_u64 v[252:253], v[86:87], 0, v[242:243]
	s_waitcnt lgkmcnt(0)
	s_barrier
	ds_read_b128 v[244:247], v241
	ds_read_b128 v[248:251], v241 offset:1056
	s_waitcnt lgkmcnt(0)
	s_barrier
	global_store_dwordx4 v[252:253], v[244:247], off offset:-2048
	global_store_dwordx4 v[252:253], v[248:251], off offset:2048
	s_and_saveexec_b64 s[50:51], s[0:1]
	s_cbranch_execz .LBB0_1494
	s_waitcnt lgkmcnt(0)
	v_add_f32_e32 v80, v80, v81
	ds_write_b32 v231, v80 offset:320
.LBB0_1494:
	s_or_b64 exec, exec, s[50:51]
	s_waitcnt vmcnt(10)
	v_pk_fma_f32 v[76:77], v[76:77], v[128:129], v[156:157]
	s_waitcnt vmcnt(8)
	v_pk_fma_f32 v[72:73], v[72:73], v[116:117], v[148:149]
	v_mul_f32_e32 v84, v77, v77
	v_pk_fma_f32 v[82:83], v[56:57], v[124:125], v[152:153]
	v_cvt_pk_bf16_f32 v56, v76, v77
	v_fmac_f32_e32 v84, v76, v76
	v_pk_fma_f32 v[76:77], v[70:71], v[114:115], v[146:147]
	v_pk_fma_f32 v[70:71], v[68:69], v[112:113], v[144:145]
	v_mul_f32_e32 v68, v73, v73
	v_pk_fma_f32 v[78:79], v[78:79], v[130:131], v[158:159]
	v_pk_fma_f32 v[74:75], v[74:75], v[118:119], v[150:151]
	v_fmac_f32_e32 v68, v72, v72
	v_fmac_f32_e32 v84, v78, v78
	v_fmac_f32_e32 v68, v74, v74
	v_fmac_f32_e32 v84, v79, v79
	v_fmac_f32_e32 v68, v75, v75
	s_waitcnt lgkmcnt(0)
	v_lshlrev_b64 v[80:81], 11, v[218:219]
	s_mov_b64 s[50:51], 0x50000
	v_fmac_f32_e32 v84, v82, v82
	v_fmac_f32_e32 v68, v70, v70
	v_lshl_add_u64 v[120:121], v[80:81], 0, s[50:51]
	v_pk_fma_f32 v[80:81], v[58:59], v[126:127], v[154:155]
	v_fmac_f32_e32 v84, v83, v83
	v_fmac_f32_e32 v68, v71, v71
	v_fmac_f32_e32 v84, v80, v80
	v_fmac_f32_e32 v68, v76, v76
	v_fmac_f32_e32 v84, v81, v81
	v_fmac_f32_e32 v68, v77, v77
	v_cvt_pk_bf16_f32 v57, v78, v79
	v_cvt_pk_bf16_f32 v58, v82, v83
	v_cvt_pk_bf16_f32 v59, v80, v81
	v_add_f32_e32 v80, v84, v68
	ds_bpermute_b32 v81, v238, v80
	v_lshl_add_u64 v[68:69], s[6:7], 0, v[120:121]
	v_lshl_add_u64 v[78:79], v[208:209], 1, v[68:69]
	ds_write_b128 v240, v[56:59]
	v_cvt_pk_bf16_f32 v68, v72, v73
	s_waitcnt lgkmcnt(0)
	v_add_f32_e32 v72, v80, v81
	ds_bpermute_b32 v73, v239, v72
	v_cvt_pk_bf16_f32 v69, v74, v75
	v_cvt_pk_bf16_f32 v70, v70, v71
	v_cvt_pk_bf16_f32 v71, v76, v77
	ds_write_b128 v240, v[68:71] offset:256
	v_lshl_add_u64 v[252:253], v[78:79], 0, v[242:243]
	s_waitcnt lgkmcnt(0)
	s_barrier
	ds_read_b128 v[244:247], v241
	ds_read_b128 v[248:251], v241 offset:1056
	s_waitcnt lgkmcnt(0)
	s_barrier
	global_store_dwordx4 v[252:253], v[244:247], off offset:-2048
	global_store_dwordx4 v[252:253], v[248:251], off offset:2048
	s_and_saveexec_b64 s[50:51], s[0:1]
	s_cbranch_execz .LBB0_1496
	s_waitcnt lgkmcnt(0)
	v_add_f32_e32 v72, v72, v73
	ds_write_b32 v231, v72 offset:384
.LBB0_1496:
	s_or_b64 exec, exec, s[50:51]
	s_waitcnt vmcnt(8)
	v_pk_fma_f32 v[64:65], v[64:65], v[128:129], v[108:109]
	s_waitcnt vmcnt(6)
	v_pk_fma_f32 v[40:41], v[40:41], v[116:117], v[100:101]
	v_mul_f32_e32 v76, v65, v65
	v_pk_fma_f32 v[74:75], v[60:61], v[124:125], v[104:105]
	v_cvt_pk_bf16_f32 v60, v64, v65
	v_fmac_f32_e32 v76, v64, v64
	v_pk_fma_f32 v[64:65], v[38:39], v[114:115], v[98:99]
	v_pk_fma_f32 v[38:39], v[36:37], v[112:113], v[96:97]
	v_mul_f32_e32 v36, v41, v41
	v_pk_fma_f32 v[66:67], v[66:67], v[130:131], v[110:111]
	v_pk_fma_f32 v[42:43], v[42:43], v[118:119], v[102:103]
	v_fmac_f32_e32 v36, v40, v40
	v_fmac_f32_e32 v76, v66, v66
	v_fmac_f32_e32 v36, v42, v42
	v_fmac_f32_e32 v76, v67, v67
	v_fmac_f32_e32 v36, v43, v43
	v_fmac_f32_e32 v76, v74, v74
	v_fmac_f32_e32 v36, v38, v38
	s_waitcnt lgkmcnt(0)
	v_pk_fma_f32 v[72:73], v[62:63], v[126:127], v[106:107]
	v_fmac_f32_e32 v76, v75, v75
	v_fmac_f32_e32 v36, v39, v39
	v_fmac_f32_e32 v76, v72, v72
	v_fmac_f32_e32 v36, v64, v64
	v_fmac_f32_e32 v76, v73, v73
	v_fmac_f32_e32 v36, v65, v65
	v_cvt_pk_bf16_f32 v61, v66, v67
	v_cvt_pk_bf16_f32 v62, v74, v75
	v_cvt_pk_bf16_f32 v63, v72, v73
	v_add_f32_e32 v72, v76, v36
	ds_bpermute_b32 v73, v238, v72
	v_lshlrev_b64 v[122:123], 11, v[166:167]
	v_lshl_add_u64 v[36:37], s[6:7], 0, v[122:123]
	v_lshl_add_u64 v[66:67], v[208:209], 1, v[36:37]
	ds_write_b128 v240, v[60:63]
	v_cvt_pk_bf16_f32 v36, v40, v41
	s_waitcnt lgkmcnt(0)
	v_add_f32_e32 v40, v72, v73
	ds_bpermute_b32 v41, v239, v40
	v_cvt_pk_bf16_f32 v37, v42, v43
	v_cvt_pk_bf16_f32 v38, v38, v39
	v_cvt_pk_bf16_f32 v39, v64, v65
	ds_write_b128 v240, v[36:39] offset:256
	v_lshl_add_u64 v[252:253], v[66:67], 0, v[242:243]
	s_waitcnt lgkmcnt(0)
	s_barrier
	ds_read_b128 v[244:247], v241
	ds_read_b128 v[248:251], v241 offset:1056
	s_waitcnt lgkmcnt(0)
	s_barrier
	global_store_dwordx4 v[252:253], v[244:247], off offset:-2048
	global_store_dwordx4 v[252:253], v[248:251], off offset:2048
	s_and_saveexec_b64 s[50:51], s[0:1]
	s_cbranch_execz .LBB0_1498
	s_waitcnt lgkmcnt(0)
	v_add_f32_e32 v40, v40, v41
	ds_write_b32 v231, v40 offset:448
